# removed 63 more sNaN-quieting v_max x,x canonicalizes (in-place or folded into their single fmax consumer) in attn0/attn1/attn2/index
# speedup vs baseline: 1.0066x; 1.0066x over previous
; DI void phase_scan(const Params& p, unsigned char* lds) {
;     ...
;         for (int u = blockIdx.x; u < 256; u += gridDim.x) {
;             const int bh = u >> 3, b = bh >> 3, h = bh & 7, chunk = u & 7;
;             float qm = 0.f, km = 0.f;
; #pragma unroll
;             for (int j = 0; j < 2; ++j) {
;                 const int s = chunk * 1024 + j * 512 + (int)threadIdx.x;
;                 const bf16_t* row = P + (size_t)(b * SEQ + s) * P0_PITCH + h * 64;
;                 float qs = 0.f, ks = 0.f;
; #pragma unroll
;                 for (int c = 0; c < 8; ++c) {
;                     const u32x4 qv = *(const u32x4*)(row + 1536 + c * 8), kv = *(const u32x4*)(row + 2048 + c * 8);
; #pragma unroll
;                     for (int e = 0; e < 4; ++e) {
;                         const float q0 = __uint_as_float(qv[e] << 16), q1 = __uint_as_float(qv[e] & 0xffff0000u);
;                         const float k0 = __uint_as_float(kv[e] << 16), k1 = __uint_as_float(kv[e] & 0xffff0000u);
;                         qs += q0 * q0 + q1 * q1; ks += k0 * k0 + k1 * k1;
;                     }
.LBB0_1211:
	s_lshl_b32 s0, s18, 10
	s_lshl_b32 s1, s18, 7
	s_and_b32 s0, s0, 0x1c00
	s_and_b32 s1, s1, 0xffffe000
	s_ashr_i32 s10, s18, 3
	s_or_b32 s0, s1, s0
	v_or_b32_e32 v32, s0, v1
	s_lshl_b32 s0, s10, 7
	s_and_b32 s0, s0, 0x380
	s_add_u32 s0, s12, s0
	s_addc_u32 s1, s13, 0
	v_mov_b64_e32 v[18:19], s[0:1]
	v_mad_i64_i32 v[20:21], s[0:1], v32, s16, v[18:19]
	v_add_co_u32_e64 v22, s[2:3], s17, v20
	global_load_dwordx4 v[34:37], v[20:21], off offset:3072
	global_load_dwordx4 v[38:41], v[20:21], off offset:3088
	v_addc_co_u32_e64 v23, s[2:3], 0, v21, s[2:3]
	global_load_dwordx4 v[42:45], v[22:23], off
	v_lshl_add_u64 v[50:51], v[20:21], 0, s[4:5]
	global_load_dwordx4 v[46:49], v[50:51], off offset:16
	global_load_dwordx4 v[10:13], v[50:51], off offset:32
	s_waitcnt lgkmcnt(0)
	global_load_dwordx4 v[2:5], v[20:21], off offset:3120
	global_load_dwordx4 v[14:17], v[20:21], off offset:3104
	global_load_dwordx4 v[6:9], v[50:51], off offset:48
	s_waitcnt vmcnt(0)
	v_lshlrev_b32_e32 v33, 16, v34
	v_and_b32_e32 v34, 0xffff0000, v34
	v_lshlrev_b32_e32 v50, 16, v35
	v_and_b32_e32 v35, 0xffff0000, v35
	v_lshlrev_b32_e32 v51, 16, v36
	v_and_b32_e32 v36, 0xffff0000, v36
	v_lshlrev_b32_e32 v57, 16, v42
	v_and_b32_e32 v42, 0xffff0000, v42
	v_mul_f32_e32 v34, v34, v34
	v_lshlrev_b32_e32 v58, 16, v43
	v_and_b32_e32 v43, 0xffff0000, v43
	v_mul_f32_e32 v35, v35, v35
	v_lshlrev_b32_e32 v52, 16, v37
	v_and_b32_e32 v37, 0xffff0000, v37
	v_lshlrev_b32_e32 v59, 16, v44
	v_and_b32_e32 v44, 0xffff0000, v44
	v_mul_f32_e32 v36, v36, v36
	v_fmac_f32_e32 v34, v33, v33
	v_mul_f32_e32 v33, v42, v42
	v_fmac_f32_e32 v35, v50, v50
	v_mul_f32_e32 v42, v43, v43
	v_lshlrev_b32_e32 v53, 16, v38
	v_and_b32_e32 v38, 0xffff0000, v38
	v_lshlrev_b32_e32 v60, 16, v45
	v_and_b32_e32 v45, 0xffff0000, v45
	v_mul_f32_e32 v37, v37, v37
	v_fmac_f32_e32 v36, v51, v51
	v_mul_f32_e32 v43, v44, v44
	v_fmac_f32_e32 v33, v57, v57
	v_add_f32_e32 v34, v34, v35
	v_fmac_f32_e32 v42, v58, v58
	v_lshlrev_b32_e32 v54, 16, v39
	v_and_b32_e32 v39, 0xffff0000, v39
	v_lshlrev_b32_e32 v61, 16, v46
	v_and_b32_e32 v46, 0xffff0000, v46
	v_mul_f32_e32 v38, v38, v38
	v_fmac_f32_e32 v37, v52, v52
	v_mul_f32_e32 v44, v45, v45
	v_fmac_f32_e32 v43, v59, v59
	v_add_f32_e32 v33, v33, v42
	v_add_f32_e32 v34, v36, v34
	v_lshlrev_b32_e32 v55, 16, v40
	v_and_b32_e32 v40, 0xffff0000, v40
	v_lshlrev_b32_e32 v62, 16, v47
	v_and_b32_e32 v47, 0xffff0000, v47
	v_mul_f32_e32 v39, v39, v39
	v_fmac_f32_e32 v38, v53, v53
	v_mul_f32_e32 v45, v46, v46
	v_fmac_f32_e32 v44, v60, v60
	v_add_f32_e32 v33, v43, v33
	v_add_f32_e32 v34, v37, v34
	v_and_b32_e32 v36, 0xffff0000, v49
	v_lshlrev_b32_e32 v56, 16, v41
	v_and_b32_e32 v41, 0xffff0000, v41
	v_lshlrev_b32_e32 v63, 16, v48
	v_and_b32_e32 v48, 0xffff0000, v48
	v_mul_f32_e32 v40, v40, v40
	v_fmac_f32_e32 v39, v54, v54
	v_mul_f32_e32 v46, v47, v47
	v_fmac_f32_e32 v45, v61, v61
	v_add_f32_e32 v33, v44, v33
	v_add_f32_e32 v34, v38, v34
	v_lshlrev_b32_e32 v35, 16, v49
	v_mul_f32_e32 v36, v36, v36
	v_fmac_f32_e32 v40, v55, v55
	v_mul_f32_e32 v47, v48, v48
	v_fmac_f32_e32 v46, v62, v62
	v_add_f32_e32 v33, v45, v33
	v_add_f32_e32 v34, v39, v34
	v_mul_f32_e32 v37, v41, v41
	v_fmac_f32_e32 v36, v35, v35
	v_lshlrev_b32_e32 v35, 16, v14
	v_and_b32_e32 v14, 0xffff0000, v14
	v_fmac_f32_e32 v47, v63, v63
	v_add_f32_e32 v33, v46, v33
	v_add_f32_e32 v34, v40, v34
	v_fmac_f32_e32 v37, v56, v56
	v_mul_f32_e32 v14, v14, v14
	v_add_f32_e32 v33, v47, v33
	v_add_f32_e32 v34, v37, v34
	v_lshlrev_b32_e32 v42, 16, v10
	v_and_b32_e32 v10, 0xffff0000, v10
	v_fmac_f32_e32 v14, v35, v35
	v_add_f32_e32 v33, v36, v33
	v_add_f32_e32 v14, v14, v34
	v_mul_f32_e32 v10, v10, v10
	global_load_dwordx4 v[34:37], v[20:21], off offset:3152
	global_load_dwordx4 v[38:41], v[20:21], off offset:3136
	v_fmac_f32_e32 v10, v42, v42
	global_load_dwordx4 v[42:45], v[22:23], off offset:64
	v_lshlrev_b32_e32 v22, 16, v15
	v_and_b32_e32 v15, 0xffff0000, v15
	v_lshlrev_b32_e32 v23, 16, v11
	v_and_b32_e32 v11, 0xffff0000, v11
	v_mul_f32_e32 v15, v15, v15
	v_fmac_f32_e32 v15, v22, v22
	v_mul_f32_e32 v11, v11, v11
	v_add_f32_e32 v10, v10, v33
	v_add_f32_e32 v14, v15, v14
	v_fmac_f32_e32 v11, v23, v23
	v_and_b32_e32 v15, 0xffff0000, v16
	v_add_f32_e32 v10, v11, v10
	v_lshlrev_b32_e32 v11, 16, v16
	v_lshlrev_b32_e32 v16, 16, v12
	v_and_b32_e32 v12, 0xffff0000, v12
	v_mul_f32_e32 v15, v15, v15
	v_fmac_f32_e32 v15, v11, v11
	v_mul_f32_e32 v12, v12, v12
	v_add_f32_e32 v11, v15, v14
	v_fmac_f32_e32 v12, v16, v16
	v_and_b32_e32 v14, 0xffff0000, v17
	v_add_f32_e32 v10, v12, v10
	v_lshlrev_b32_e32 v12, 16, v17
	v_lshlrev_b32_e32 v15, 16, v13
	v_and_b32_e32 v13, 0xffff0000, v13
	v_mul_f32_e32 v14, v14, v14
	v_fmac_f32_e32 v14, v12, v12
	v_mul_f32_e32 v12, v13, v13
	v_lshlrev_b32_e32 v17, 16, v6
	v_and_b32_e32 v6, 0xffff0000, v6
	v_fmac_f32_e32 v12, v15, v15
	v_mul_f32_e32 v6, v6, v6
	v_add_f32_e32 v16, v12, v10
	v_lshlrev_b32_e32 v10, 16, v2
	v_and_b32_e32 v2, 0xffff0000, v2
	v_fmac_f32_e32 v6, v17, v17
	v_mul_f32_e32 v2, v2, v2
	v_add_f32_e32 v6, v6, v16
	v_lshlrev_b32_e32 v16, 16, v3
	v_and_b32_e32 v3, 0xffff0000, v3
	v_add_f32_e32 v11, v14, v11
	v_fmac_f32_e32 v2, v10, v10
	v_mul_f32_e32 v3, v3, v3
	v_add_f32_e32 v2, v2, v11
	v_lshl_add_u64 v[14:15], v[20:21], 0, s[6:7]
	v_lshlrev_b32_e32 v17, 16, v7
	v_and_b32_e32 v7, 0xffff0000, v7
	v_fmac_f32_e32 v3, v16, v16
	global_load_dwordx4 v[10:13], v[14:15], off offset:16
	v_add_f32_e32 v2, v3, v2
	v_mul_f32_e32 v3, v7, v7
	v_fmac_f32_e32 v3, v17, v17
	v_add_f32_e32 v3, v3, v6
	v_lshlrev_b32_e32 v6, 16, v4
	v_and_b32_e32 v4, 0xffff0000, v4
	v_mul_f32_e32 v4, v4, v4
	v_lshlrev_b32_e32 v7, 16, v8
	v_and_b32_e32 v8, 0xffff0000, v8
	v_fmac_f32_e32 v4, v6, v6
	v_add_f32_e32 v2, v4, v2
	v_mul_f32_e32 v4, v8, v8
	v_fmac_f32_e32 v4, v7, v7
	v_add_f32_e32 v3, v4, v3
	v_lshlrev_b32_e32 v4, 16, v5
	v_and_b32_e32 v5, 0xffff0000, v5
	v_mul_f32_e32 v5, v5, v5
	v_and_b32_e32 v7, 0xffff0000, v9
	v_fmac_f32_e32 v5, v4, v4
	v_lshlrev_b32_e32 v6, 16, v9
	v_add_f32_e32 v16, v5, v2
	v_mul_f32_e32 v2, v7, v7
	v_fmac_f32_e32 v2, v6, v6
	v_add_f32_e32 v17, v2, v3
	global_load_dwordx4 v[2:5], v[20:21], off offset:3184
	global_load_dwordx4 v[46:49], v[20:21], off offset:3168
	global_load_dwordx4 v[6:9], v[14:15], off offset:48
	global_load_dwordx4 v[50:53], v[14:15], off offset:32
	s_waitcnt vmcnt(6)
; DI void phase_scan(const Params& p, unsigned char* lds) {
;     ...
;                 for (int c = 0; c < 8; ++c) {
;                     const u32x4 qv = *(const u32x4*)(row + 1536 + c * 8), kv = *(const u32x4*)(row + 2048 + c * 8);
; #pragma unroll
;                     for (int e = 0; e < 4; ++e) {
;                         const float q0 = __uint_as_float(qv[e] << 16), q1 = __uint_as_float(qv[e] & 0xffff0000u);
;                         const float k0 = __uint_as_float(kv[e] << 16), k1 = __uint_as_float(kv[e] & 0xffff0000u);
;                         qs += q0 * q0 + q1 * q1; ks += k0 * k0 + k1 * k1;
;                     }
	v_and_b32_e32 v15, 0xffff0000, v38
	v_lshlrev_b32_e32 v14, 16, v38
	v_mul_f32_e32 v15, v15, v15
	s_waitcnt vmcnt(5)
	v_and_b32_e32 v21, 0xffff0000, v42
	v_fmac_f32_e32 v15, v14, v14
	v_lshlrev_b32_e32 v20, 16, v42
	v_add_f32_e32 v14, v15, v16
	v_mul_f32_e32 v15, v21, v21
	v_fmac_f32_e32 v15, v20, v20
	v_add_f32_e32 v15, v15, v17
	v_and_b32_e32 v17, 0xffff0000, v39
	v_lshlrev_b32_e32 v16, 16, v39
	v_and_b32_e32 v21, 0xffff0000, v43
	v_mul_f32_e32 v17, v17, v17
	v_lshlrev_b32_e32 v20, 16, v43
	v_fmac_f32_e32 v17, v16, v16
	v_mul_f32_e32 v16, v21, v21
	v_add_f32_e32 v14, v17, v14
	v_fmac_f32_e32 v16, v20, v20
	v_and_b32_e32 v17, 0xffff0000, v40
	v_add_f32_e32 v15, v16, v15
	v_lshlrev_b32_e32 v16, 16, v40
	v_and_b32_e32 v21, 0xffff0000, v44
	v_mul_f32_e32 v17, v17, v17
	v_lshlrev_b32_e32 v20, 16, v44
	v_fmac_f32_e32 v17, v16, v16
	v_mul_f32_e32 v16, v21, v21
	v_add_f32_e32 v14, v17, v14
	v_fmac_f32_e32 v16, v20, v20
	v_and_b32_e32 v17, 0xffff0000, v41
	v_add_f32_e32 v15, v16, v15
	v_lshlrev_b32_e32 v16, 16, v41
	v_and_b32_e32 v21, 0xffff0000, v45
	v_mul_f32_e32 v17, v17, v17
	v_lshlrev_b32_e32 v20, 16, v45
	v_fmac_f32_e32 v17, v16, v16
	v_mul_f32_e32 v16, v21, v21
	v_add_f32_e32 v14, v17, v14
	v_fmac_f32_e32 v16, v20, v20
	v_and_b32_e32 v17, 0xffff0000, v34
	v_add_f32_e32 v15, v16, v15
	v_lshlrev_b32_e32 v16, 16, v34
	v_mul_f32_e32 v17, v17, v17
	v_fmac_f32_e32 v17, v16, v16
	v_add_f32_e32 v14, v17, v14
	v_and_b32_e32 v16, 0xffff0000, v35
	v_mul_f32_e32 v16, v16, v16
	s_waitcnt vmcnt(4)
	v_lshlrev_b32_e32 v20, 16, v10
	v_and_b32_e32 v10, 0xffff0000, v10
	v_mul_f32_e32 v10, v10, v10
	v_fmac_f32_e32 v10, v20, v20
	v_lshlrev_b32_e32 v17, 16, v11
	v_and_b32_e32 v11, 0xffff0000, v11
	v_add_f32_e32 v10, v10, v15
	v_lshlrev_b32_e32 v15, 16, v35
	v_mul_f32_e32 v11, v11, v11
	v_fmac_f32_e32 v16, v15, v15
	v_fmac_f32_e32 v11, v17, v17
	v_and_b32_e32 v15, 0xffff0000, v36
	v_add_f32_e32 v14, v16, v14
	v_add_f32_e32 v10, v11, v10
	v_lshlrev_b32_e32 v11, 16, v36
	v_lshlrev_b32_e32 v16, 16, v12
	v_and_b32_e32 v12, 0xffff0000, v12
	v_mul_f32_e32 v15, v15, v15
	v_fmac_f32_e32 v15, v11, v11
	v_mul_f32_e32 v12, v12, v12
	v_add_f32_e32 v11, v15, v14
	v_fmac_f32_e32 v12, v16, v16
	v_and_b32_e32 v14, 0xffff0000, v37
	v_add_f32_e32 v10, v12, v10
	v_lshlrev_b32_e32 v12, 16, v37
	v_lshlrev_b32_e32 v15, 16, v13
	v_and_b32_e32 v13, 0xffff0000, v13
	v_mul_f32_e32 v14, v14, v14
	v_fmac_f32_e32 v14, v12, v12
	v_mul_f32_e32 v12, v13, v13
	v_fmac_f32_e32 v12, v15, v15
	s_waitcnt vmcnt(2)
	v_and_b32_e32 v13, 0xffff0000, v46
	v_add_f32_e32 v10, v12, v10
	v_lshlrev_b32_e32 v12, 16, v46
	v_mul_f32_e32 v13, v13, v13
	v_add_f32_e32 v11, v14, v11
	s_waitcnt vmcnt(0)
	v_and_b32_e32 v15, 0xffff0000, v50
	v_fmac_f32_e32 v13, v12, v12
	v_lshlrev_b32_e32 v14, 16, v50
	v_add_f32_e32 v11, v13, v11
	v_mul_f32_e32 v12, v15, v15
	v_add_u32_e32 v13, 0x200, v32
	v_fmac_f32_e32 v12, v14, v14
	v_mad_i64_i32 v[14:15], s[0:1], v13, s16, v[18:19]
	v_add_co_u32_e64 v16, s[2:3], s17, v14
	global_load_dwordx4 v[18:21], v[14:15], off offset:3088
	global_load_dwordx4 v[32:35], v[14:15], off offset:3072
	v_addc_co_u32_e64 v17, s[2:3], 0, v15, s[2:3]
	global_load_dwordx4 v[36:39], v[16:17], off
	v_and_b32_e32 v13, 0xffff0000, v47
	v_add_f32_e32 v10, v12, v10
	v_lshlrev_b32_e32 v12, 16, v47
	v_and_b32_e32 v23, 0xffff0000, v51
	v_mul_f32_e32 v13, v13, v13
	v_lshlrev_b32_e32 v22, 16, v51
	v_fmac_f32_e32 v13, v12, v12
	v_mul_f32_e32 v12, v23, v23
	v_add_f32_e32 v11, v13, v11
	v_fmac_f32_e32 v12, v22, v22
	v_and_b32_e32 v13, 0xffff0000, v48
	v_add_f32_e32 v10, v12, v10
	v_lshlrev_b32_e32 v12, 16, v48
	v_and_b32_e32 v23, 0xffff0000, v52
	v_mul_f32_e32 v13, v13, v13
	v_lshlrev_b32_e32 v22, 16, v52
	v_fmac_f32_e32 v13, v12, v12
	v_mul_f32_e32 v12, v23, v23
	v_add_f32_e32 v11, v13, v11
	v_fmac_f32_e32 v12, v22, v22
	v_and_b32_e32 v13, 0xffff0000, v49
	v_add_f32_e32 v10, v12, v10
	v_lshlrev_b32_e32 v12, 16, v49
	v_mul_f32_e32 v13, v13, v13
	v_and_b32_e32 v23, 0xffff0000, v53
	v_fmac_f32_e32 v13, v12, v12
	v_lshlrev_b32_e32 v22, 16, v53
	v_add_f32_e32 v44, v13, v11
	v_mul_f32_e32 v11, v23, v23
	v_fmac_f32_e32 v11, v22, v22
	v_lshl_add_u64 v[22:23], v[14:15], 0, s[4:5]
	v_add_f32_e32 v45, v11, v10
	v_lshlrev_b32_e32 v46, 16, v2
	v_and_b32_e32 v2, 0xffff0000, v2
	global_load_dwordx4 v[10:13], v[22:23], off offset:32
	global_load_dwordx4 v[40:43], v[22:23], off offset:16
	v_mul_f32_e32 v2, v2, v2
	v_lshlrev_b32_e32 v47, 16, v6
	v_and_b32_e32 v6, 0xffff0000, v6
	v_fmac_f32_e32 v2, v46, v46
	v_add_f32_e32 v2, v2, v44
	v_mul_f32_e32 v6, v6, v6
	v_lshlrev_b32_e32 v44, 16, v3
	v_and_b32_e32 v3, 0xffff0000, v3
	v_fmac_f32_e32 v6, v47, v47
	v_mul_f32_e32 v3, v3, v3
	v_add_f32_e32 v6, v6, v45
	v_lshlrev_b32_e32 v45, 16, v7
	v_and_b32_e32 v7, 0xffff0000, v7
	v_fmac_f32_e32 v3, v44, v44
	v_add_f32_e32 v2, v3, v2
	v_mul_f32_e32 v3, v7, v7
	v_fmac_f32_e32 v3, v45, v45
	v_add_f32_e32 v3, v3, v6
	v_lshlrev_b32_e32 v6, 16, v4
	v_and_b32_e32 v4, 0xffff0000, v4
	v_mul_f32_e32 v4, v4, v4
	v_lshlrev_b32_e32 v7, 16, v8
	v_and_b32_e32 v8, 0xffff0000, v8
	v_fmac_f32_e32 v4, v6, v6
	v_add_f32_e32 v2, v4, v2
	v_mul_f32_e32 v4, v8, v8
	v_fmac_f32_e32 v4, v7, v7
	v_add_f32_e32 v3, v4, v3
	v_lshlrev_b32_e32 v4, 16, v5
	v_and_b32_e32 v5, 0xffff0000, v5
	v_mul_f32_e32 v5, v5, v5
	v_and_b32_e32 v7, 0xffff0000, v9
	v_fmac_f32_e32 v5, v4, v4
	v_lshlrev_b32_e32 v6, 16, v9
	v_add_f32_e32 v48, v5, v2
	v_mul_f32_e32 v2, v7, v7
	v_fmac_f32_e32 v2, v6, v6
	v_add_f32_e32 v49, v2, v3
	global_load_dwordx4 v[2:5], v[14:15], off offset:3120
	global_load_dwordx4 v[44:47], v[14:15], off offset:3104
	global_load_dwordx4 v[6:9], v[22:23], off offset:48
	s_waitcnt vmcnt(6)
; DI void phase_scan(const Params& p, unsigned char* lds) {
;     ...
;             for (int j = 0; j < 2; ++j) {
;                 const int s = chunk * 1024 + j * 512 + (int)threadIdx.x;
;                 const bf16_t* row = P + (size_t)(b * SEQ + s) * P0_PITCH + h * 64;
;                 float qs = 0.f, ks = 0.f;
; #pragma unroll
;                 for (int c = 0; c < 8; ++c) {
;                     const u32x4 qv = *(const u32x4*)(row + 1536 + c * 8), kv = *(const u32x4*)(row + 2048 + c * 8);
; #pragma unroll
;                     for (int e = 0; e < 4; ++e) {
;                         const float q0 = __uint_as_float(qv[e] << 16), q1 = __uint_as_float(qv[e] & 0xffff0000u);
;                         const float k0 = __uint_as_float(kv[e] << 16), k1 = __uint_as_float(kv[e] & 0xffff0000u);
;                         qs += q0 * q0 + q1 * q1; ks += k0 * k0 + k1 * k1;
;                     }
;                 }
;                 qm = fmaxf(qm, qs); km = fmaxf(km, ks);
	v_and_b32_e32 v23, 0xffff0000, v32
	v_lshlrev_b32_e32 v22, 16, v32
	v_mul_f32_e32 v23, v23, v23
	s_waitcnt vmcnt(5)
	v_lshlrev_b32_e32 v32, 16, v36
	v_and_b32_e32 v36, 0xffff0000, v36
	v_fmac_f32_e32 v23, v22, v22
	v_mul_f32_e32 v22, v36, v36
	v_fmac_f32_e32 v22, v32, v32
	v_lshlrev_b32_e32 v32, 16, v33
	v_and_b32_e32 v33, 0xffff0000, v33
	v_lshlrev_b32_e32 v36, 16, v37
	v_and_b32_e32 v37, 0xffff0000, v37
	v_mul_f32_e32 v33, v33, v33
	v_fmac_f32_e32 v33, v32, v32
	v_mul_f32_e32 v32, v37, v37
	v_add_f32_e32 v23, v23, v33
	v_fmac_f32_e32 v32, v36, v36
	v_and_b32_e32 v33, 0xffff0000, v34
	v_add_f32_e32 v22, v22, v32
	v_lshlrev_b32_e32 v32, 16, v34
	v_and_b32_e32 v36, 0xffff0000, v38
	v_mul_f32_e32 v33, v33, v33
	v_lshlrev_b32_e32 v34, 16, v38
	v_fmac_f32_e32 v33, v32, v32
	v_mul_f32_e32 v32, v36, v36
	v_add_f32_e32 v23, v33, v23
	v_fmac_f32_e32 v32, v34, v34
	v_and_b32_e32 v33, 0xffff0000, v35
	v_add_f32_e32 v22, v32, v22
	v_lshlrev_b32_e32 v32, 16, v35
	v_and_b32_e32 v35, 0xffff0000, v39
	v_mul_f32_e32 v33, v33, v33
	v_lshlrev_b32_e32 v34, 16, v39
	v_fmac_f32_e32 v33, v32, v32
	v_mul_f32_e32 v32, v35, v35
	v_fmac_f32_e32 v32, v34, v34
	v_add_f32_e32 v22, v32, v22
	v_lshlrev_b32_e32 v32, 16, v18
	v_and_b32_e32 v18, 0xffff0000, v18
	v_mul_f32_e32 v18, v18, v18
	v_add_f32_e32 v23, v33, v23
	s_waitcnt vmcnt(3)
	v_and_b32_e32 v34, 0xffff0000, v40
	v_fmac_f32_e32 v18, v32, v32
	v_lshlrev_b32_e32 v33, 16, v40
	v_add_f32_e32 v18, v18, v23
	v_mul_f32_e32 v23, v34, v34
	v_fmac_f32_e32 v23, v33, v33
	v_add_f32_e32 v22, v23, v22
	v_lshlrev_b32_e32 v23, 16, v19
	v_and_b32_e32 v19, 0xffff0000, v19
	v_mul_f32_e32 v19, v19, v19
	v_and_b32_e32 v33, 0xffff0000, v41
	v_fmac_f32_e32 v19, v23, v23
	v_lshlrev_b32_e32 v32, 16, v41
	v_add_f32_e32 v18, v19, v18
	v_mul_f32_e32 v19, v33, v33
	v_fmac_f32_e32 v19, v32, v32
	v_add_f32_e32 v19, v19, v22
	v_lshlrev_b32_e32 v22, 16, v20
	v_and_b32_e32 v20, 0xffff0000, v20
	v_mul_f32_e32 v20, v20, v20
	v_and_b32_e32 v32, 0xffff0000, v42
	v_fmac_f32_e32 v20, v22, v22
	v_lshlrev_b32_e32 v23, 16, v42
	v_add_f32_e32 v18, v20, v18
	v_mul_f32_e32 v20, v32, v32
	v_fmac_f32_e32 v20, v23, v23
	v_add_f32_e32 v19, v20, v19
	v_lshlrev_b32_e32 v20, 16, v21
	v_and_b32_e32 v21, 0xffff0000, v21
	v_and_b32_e32 v23, 0xffff0000, v43
	v_mul_f32_e32 v21, v21, v21
	v_lshlrev_b32_e32 v22, 16, v43
	v_fmac_f32_e32 v21, v20, v20
	v_mul_f32_e32 v20, v23, v23
	v_fmac_f32_e32 v20, v22, v22
	v_add_f32_e32 v22, v20, v19
	s_waitcnt vmcnt(1)
	v_and_b32_e32 v20, 0xffff0000, v44
	v_lshlrev_b32_e32 v19, 16, v44
	v_mul_f32_e32 v20, v20, v20
	v_add_f32_e32 v18, v21, v18
	v_lshlrev_b32_e32 v23, 16, v10
	v_and_b32_e32 v10, 0xffff0000, v10
	v_fmac_f32_e32 v20, v19, v19
	v_add_f32_e32 v40, v20, v18
	v_mul_f32_e32 v10, v10, v10
	global_load_dwordx4 v[18:21], v[14:15], off offset:3152
	global_load_dwordx4 v[32:35], v[14:15], off offset:3136
	v_fmac_f32_e32 v10, v23, v23
	global_load_dwordx4 v[36:39], v[16:17], off offset:64
	v_and_b32_e32 v17, 0xffff0000, v45
	v_add_f32_e32 v10, v10, v22
	v_lshlrev_b32_e32 v16, 16, v45
	v_lshlrev_b32_e32 v22, 16, v11
	v_and_b32_e32 v11, 0xffff0000, v11
	v_mul_f32_e32 v17, v17, v17
	v_fmac_f32_e32 v17, v16, v16
	v_mul_f32_e32 v11, v11, v11
	v_add_f32_e32 v16, v17, v40
	v_fmac_f32_e32 v11, v22, v22
	v_and_b32_e32 v17, 0xffff0000, v46
	v_add_f32_e32 v10, v11, v10
	v_lshlrev_b32_e32 v11, 16, v46
	v_lshlrev_b32_e32 v22, 16, v12
	v_and_b32_e32 v12, 0xffff0000, v12
	v_mul_f32_e32 v17, v17, v17
	v_fmac_f32_e32 v17, v11, v11
	v_mul_f32_e32 v12, v12, v12
	v_add_f32_e32 v11, v17, v16
	v_fmac_f32_e32 v12, v22, v22
	v_and_b32_e32 v16, 0xffff0000, v47
	v_add_f32_e32 v10, v12, v10
	v_lshlrev_b32_e32 v12, 16, v47
	v_lshlrev_b32_e32 v17, 16, v13
	v_and_b32_e32 v13, 0xffff0000, v13
	v_mul_f32_e32 v16, v16, v16
	v_fmac_f32_e32 v16, v12, v12
	v_mul_f32_e32 v12, v13, v13
	s_waitcnt vmcnt(3)
	v_lshlrev_b32_e32 v23, 16, v6
	v_and_b32_e32 v6, 0xffff0000, v6
	v_fmac_f32_e32 v12, v17, v17
	v_mul_f32_e32 v6, v6, v6
	v_add_f32_e32 v22, v12, v10
	v_lshlrev_b32_e32 v10, 16, v2
	v_and_b32_e32 v2, 0xffff0000, v2
	v_fmac_f32_e32 v6, v23, v23
	v_mul_f32_e32 v2, v2, v2
	v_add_f32_e32 v6, v6, v22
	v_lshlrev_b32_e32 v22, 16, v3
	v_and_b32_e32 v3, 0xffff0000, v3
	v_add_f32_e32 v11, v16, v11
	v_fmac_f32_e32 v2, v10, v10
	v_lshl_add_u64 v[16:17], v[14:15], 0, s[6:7]
	v_mul_f32_e32 v3, v3, v3
	v_add_f32_e32 v2, v2, v11
	global_load_dwordx4 v[10:13], v[16:17], off offset:16
	v_lshlrev_b32_e32 v23, 16, v7
	v_and_b32_e32 v7, 0xffff0000, v7
	v_fmac_f32_e32 v3, v22, v22
	v_add_f32_e32 v2, v3, v2
	v_mul_f32_e32 v3, v7, v7
	v_fmac_f32_e32 v3, v23, v23
	v_add_f32_e32 v3, v3, v6
	v_lshlrev_b32_e32 v6, 16, v4
	v_and_b32_e32 v4, 0xffff0000, v4
	v_mul_f32_e32 v4, v4, v4
	v_lshlrev_b32_e32 v7, 16, v8
	v_and_b32_e32 v8, 0xffff0000, v8
	v_fmac_f32_e32 v4, v6, v6
	v_add_f32_e32 v2, v4, v2
	v_mul_f32_e32 v4, v8, v8
	v_fmac_f32_e32 v4, v7, v7
	v_add_f32_e32 v3, v4, v3
	v_lshlrev_b32_e32 v4, 16, v5
	v_and_b32_e32 v5, 0xffff0000, v5
	v_mul_f32_e32 v5, v5, v5
	v_and_b32_e32 v7, 0xffff0000, v9
	v_fmac_f32_e32 v5, v4, v4
	v_lshlrev_b32_e32 v6, 16, v9
	v_add_f32_e32 v22, v5, v2
	v_mul_f32_e32 v2, v7, v7
	v_fmac_f32_e32 v2, v6, v6
	v_add_f32_e32 v23, v2, v3
	global_load_dwordx4 v[2:5], v[14:15], off offset:3184
	global_load_dwordx4 v[6:9], v[14:15], off offset:3168
	global_load_dwordx4 v[40:43], v[16:17], off offset:48
	global_load_dwordx4 v[44:47], v[16:17], off offset:32
	s_waitcnt vmcnt(6)
	v_and_b32_e32 v15, 0xffff0000, v32
	v_lshlrev_b32_e32 v14, 16, v32
	v_mul_f32_e32 v15, v15, v15
	s_waitcnt vmcnt(5)
; DI void phase_scan(const Params& p, unsigned char* lds) {
;     ...
;                         qs += q0 * q0 + q1 * q1; ks += k0 * k0 + k1 * k1;
;                     }
;                 }
;                 qm = fmaxf(qm, qs); km = fmaxf(km, ks);
;             }
; #pragma unroll
;             for (int d = 32; d >= 1; d >>= 1) { qm = fmaxf(qm, __shfl_xor(qm, d)); km = fmaxf(km, __shfl_xor(km, d)); }
;             if ((threadIdx.x & 63) == 0) { atomicMax(bnd + bh * 2, __float_as_uint(qm)); atomicMax(bnd + bh * 2 + 1, __float_as_uint(km)); }
	v_and_b32_e32 v17, 0xffff0000, v36
	v_fmac_f32_e32 v15, v14, v14
	v_lshlrev_b32_e32 v16, 16, v36
	v_add_f32_e32 v14, v15, v22
	v_mul_f32_e32 v15, v17, v17
	v_fmac_f32_e32 v15, v16, v16
	v_and_b32_e32 v17, 0xffff0000, v33
	v_add_f32_e32 v15, v15, v23
	v_lshlrev_b32_e32 v16, 16, v33
	v_and_b32_e32 v23, 0xffff0000, v37
	v_mul_f32_e32 v17, v17, v17
	v_lshlrev_b32_e32 v22, 16, v37
	v_fmac_f32_e32 v17, v16, v16
	v_mul_f32_e32 v16, v23, v23
	v_add_f32_e32 v14, v17, v14
	v_fmac_f32_e32 v16, v22, v22
	v_and_b32_e32 v17, 0xffff0000, v34
	v_add_f32_e32 v15, v16, v15
	v_lshlrev_b32_e32 v16, 16, v34
	v_and_b32_e32 v23, 0xffff0000, v38
	v_mul_f32_e32 v17, v17, v17
	v_lshlrev_b32_e32 v22, 16, v38
	v_fmac_f32_e32 v17, v16, v16
	v_mul_f32_e32 v16, v23, v23
	v_add_f32_e32 v14, v17, v14
	v_fmac_f32_e32 v16, v22, v22
	v_and_b32_e32 v17, 0xffff0000, v35
	v_add_f32_e32 v15, v16, v15
	v_lshlrev_b32_e32 v16, 16, v35
	v_and_b32_e32 v23, 0xffff0000, v39
	v_mul_f32_e32 v17, v17, v17
	v_lshlrev_b32_e32 v22, 16, v39
	v_fmac_f32_e32 v17, v16, v16
	v_mul_f32_e32 v16, v23, v23
	v_add_f32_e32 v14, v17, v14
	v_fmac_f32_e32 v16, v22, v22
	v_and_b32_e32 v17, 0xffff0000, v18
	v_add_f32_e32 v15, v16, v15
	v_lshlrev_b32_e32 v16, 16, v18
	v_mul_f32_e32 v17, v17, v17
	v_fmac_f32_e32 v17, v16, v16
	v_add_f32_e32 v14, v17, v14
	v_and_b32_e32 v16, 0xffff0000, v19
	v_mul_f32_e32 v16, v16, v16
	s_waitcnt vmcnt(4)
	v_lshlrev_b32_e32 v18, 16, v10
	v_and_b32_e32 v10, 0xffff0000, v10
	v_mul_f32_e32 v10, v10, v10
	v_fmac_f32_e32 v10, v18, v18
	v_lshlrev_b32_e32 v17, 16, v11
	v_and_b32_e32 v11, 0xffff0000, v11
	v_add_f32_e32 v10, v10, v15
	v_lshlrev_b32_e32 v15, 16, v19
	v_mul_f32_e32 v11, v11, v11
	v_fmac_f32_e32 v16, v15, v15
	v_fmac_f32_e32 v11, v17, v17
	v_and_b32_e32 v15, 0xffff0000, v20
	v_add_f32_e32 v14, v16, v14
	v_add_f32_e32 v10, v11, v10
	v_lshlrev_b32_e32 v11, 16, v20
	v_lshlrev_b32_e32 v16, 16, v12
	v_and_b32_e32 v12, 0xffff0000, v12
	v_mul_f32_e32 v15, v15, v15
	v_fmac_f32_e32 v15, v11, v11
	v_mul_f32_e32 v12, v12, v12
	v_add_f32_e32 v11, v15, v14
	v_fmac_f32_e32 v12, v16, v16
	v_and_b32_e32 v14, 0xffff0000, v21
	v_add_f32_e32 v10, v12, v10
	v_lshlrev_b32_e32 v12, 16, v21
	v_lshlrev_b32_e32 v15, 16, v13
	v_and_b32_e32 v13, 0xffff0000, v13
	v_mul_f32_e32 v14, v14, v14
	v_fmac_f32_e32 v14, v12, v12
	v_mul_f32_e32 v12, v13, v13
	v_fmac_f32_e32 v12, v15, v15
	v_add_f32_e32 v10, v12, v10
	s_waitcnt vmcnt(2)
	v_lshlrev_b32_e32 v12, 16, v6
	v_and_b32_e32 v6, 0xffff0000, v6
	v_mul_f32_e32 v6, v6, v6
	v_add_f32_e32 v11, v14, v11
	s_waitcnt vmcnt(0)
	v_and_b32_e32 v14, 0xffff0000, v44
	v_fmac_f32_e32 v6, v12, v12
	v_lshlrev_b32_e32 v13, 16, v44
	v_add_f32_e32 v6, v6, v11
	v_mul_f32_e32 v11, v14, v14
	v_fmac_f32_e32 v11, v13, v13
	v_add_f32_e32 v10, v11, v10
	v_lshlrev_b32_e32 v11, 16, v7
	v_and_b32_e32 v7, 0xffff0000, v7
	v_mul_f32_e32 v7, v7, v7
	v_and_b32_e32 v13, 0xffff0000, v45
	v_fmac_f32_e32 v7, v11, v11
	v_lshlrev_b32_e32 v12, 16, v45
	v_add_f32_e32 v6, v7, v6
	v_mul_f32_e32 v7, v13, v13
	v_fmac_f32_e32 v7, v12, v12
	v_add_f32_e32 v7, v7, v10
	v_lshlrev_b32_e32 v10, 16, v8
	v_and_b32_e32 v8, 0xffff0000, v8
	v_mul_f32_e32 v8, v8, v8
	v_and_b32_e32 v12, 0xffff0000, v46
	v_fmac_f32_e32 v8, v10, v10
	v_lshlrev_b32_e32 v11, 16, v46
	v_add_f32_e32 v6, v8, v6
	v_mul_f32_e32 v8, v12, v12
	v_fmac_f32_e32 v8, v11, v11
	v_add_f32_e32 v7, v8, v7
	v_lshlrev_b32_e32 v8, 16, v9
	v_and_b32_e32 v9, 0xffff0000, v9
	v_and_b32_e32 v11, 0xffff0000, v47
	v_mul_f32_e32 v9, v9, v9
	v_lshlrev_b32_e32 v10, 16, v47
	v_fmac_f32_e32 v9, v8, v8
	v_mul_f32_e32 v8, v11, v11
	v_fmac_f32_e32 v8, v10, v10
	v_add_f32_e32 v7, v8, v7
	v_lshlrev_b32_e32 v8, 16, v2
	v_and_b32_e32 v2, 0xffff0000, v2
	v_mul_f32_e32 v2, v2, v2
	v_add_f32_e32 v6, v9, v6
	v_and_b32_e32 v10, 0xffff0000, v40
	v_fmac_f32_e32 v2, v8, v8
	v_lshlrev_b32_e32 v9, 16, v40
	v_add_f32_e32 v2, v2, v6
	v_mul_f32_e32 v6, v10, v10
	v_fmac_f32_e32 v6, v9, v9
	v_add_f32_e32 v6, v6, v7
	v_lshlrev_b32_e32 v7, 16, v3
	v_and_b32_e32 v3, 0xffff0000, v3
	v_mul_f32_e32 v3, v3, v3
	v_and_b32_e32 v9, 0xffff0000, v41
	v_fmac_f32_e32 v3, v7, v7
	v_lshlrev_b32_e32 v8, 16, v41
	v_add_f32_e32 v2, v3, v2
	v_mul_f32_e32 v3, v9, v9
	v_fmac_f32_e32 v3, v8, v8
	v_add_f32_e32 v3, v3, v6
	v_lshlrev_b32_e32 v6, 16, v4
	v_and_b32_e32 v4, 0xffff0000, v4
	v_mul_f32_e32 v4, v4, v4
	v_and_b32_e32 v8, 0xffff0000, v42
	v_fmac_f32_e32 v4, v6, v6
	v_lshlrev_b32_e32 v7, 16, v42
	v_add_f32_e32 v2, v4, v2
	v_mul_f32_e32 v4, v8, v8
	v_fmac_f32_e32 v4, v7, v7
	v_add_f32_e32 v3, v4, v3
	v_lshlrev_b32_e32 v4, 16, v5
	v_and_b32_e32 v5, 0xffff0000, v5
	v_and_b32_e32 v7, 0xffff0000, v43
	v_mul_f32_e32 v5, v5, v5
	v_lshlrev_b32_e32 v6, 16, v43
	v_fmac_f32_e32 v5, v4, v4
	v_mul_f32_e32 v4, v7, v7
	v_add_f32_e32 v2, v5, v2
	v_fmac_f32_e32 v4, v6, v6
	v_add_f32_e32 v3, v4, v3
	v_max3_f32 v2, v48, 0, v2
	ds_bpermute_b32 v4, v25, v2
	v_max3_f32 v3, v49, 0, v3
	ds_bpermute_b32 v5, v25, v3
	s_waitcnt lgkmcnt(1)
	v_max_f32_e32 v2, v2, v4
	s_waitcnt lgkmcnt(0)
	v_max_f32_e32 v4, v5, v5
	ds_bpermute_b32 v5, v26, v2
	v_max_f32_e32 v3, v3, v4
	ds_bpermute_b32 v4, v26, v3
	s_waitcnt lgkmcnt(1)
	v_max_f32_e32 v2, v2, v5
	s_waitcnt lgkmcnt(0)
	ds_bpermute_b32 v5, v27, v2
	v_max_f32_e32 v3, v3, v4
	ds_bpermute_b32 v4, v27, v3
	s_waitcnt lgkmcnt(1)
	v_max_f32_e32 v2, v2, v5
	s_waitcnt lgkmcnt(0)
	ds_bpermute_b32 v5, v28, v2
	v_max_f32_e32 v3, v3, v4
	ds_bpermute_b32 v4, v28, v3
	s_waitcnt lgkmcnt(1)
	v_max_f32_e32 v2, v2, v5
	s_waitcnt lgkmcnt(0)
	ds_bpermute_b32 v5, v29, v2
	v_max_f32_e32 v3, v3, v4
	ds_bpermute_b32 v6, v29, v3
	s_waitcnt lgkmcnt(1)
	v_max_f32_e32 v4, v2, v5
	s_waitcnt lgkmcnt(0)
	v_max_f32_e32 v2, v3, v6
	ds_bpermute_b32 v5, v30, v4
	ds_bpermute_b32 v3, v30, v2
	s_and_saveexec_b64 s[8:9], vcc
	s_cbranch_execz .LBB0_1210
	s_waitcnt lgkmcnt(1)
	s_mov_b64 s[2:3], exec
	v_max_f32_e32 v4, v4, v5
	s_mov_b32 s0, 0

; DI void phase_scan(const Params& p, unsigned char* lds) {
;     ...
;             for (int d = 32; d >= 1; d >>= 1) { qm = fmaxf(qm, __shfl_xor(qm, d)); km = fmaxf(km, __shfl_xor(km, d)); }
;             if ((threadIdx.x & 63) == 0) { atomicMax(bnd + bh * 2, __float_as_uint(qm)); atomicMax(bnd + bh * 2 + 1, __float_as_uint(km)); }
.LBB0_1216:
	s_or_b64 exec, exec, s[2:3]
	s_waitcnt lgkmcnt(0)
	s_mov_b64 s[2:3], exec
	v_max_f32_e32 v2, v2, v3
	s_mov_b32 s0, 0

; DI unsigned pk_bf16(float a, float b) { f32x2 v = {a, b}; bf2_t r = __builtin_convertvector(v, bf2_t); return __builtin_bit_cast(unsigned, r); }
; DI float xhalf_max(float v) { const auto r = __builtin_amdgcn_permlane32_swap(__float_as_uint(v), __float_as_uint(v), false, false); return fmaxf(__uint_as_float(r[0]), __uint_as_float(r[1])); }
;     ...
;             float mx = s[0][0];
; #pragma unroll
;             for (int i = 1; i < 16; ++i) mx = fmaxf(mx, s[0][i]);
; #pragma unroll
;             for (int i = 0; i < 16; ++i) mx = fmaxf(mx, s[1][i]);
;             mx = xhalf_max(mx);
;             const float mabs = mi + mx;
;             const bool up = mabs > m + 8.0f;
;             const float mn = up ? __uint_as_float(pk_bf16(mabs, 0.f) << 16) : m;
;             const float shift = mn - mi;
;             if (__ballot(shift != 0.f) != 0) {
;                 if (__ballot(up) != 0) {
;                     const float alpha = __builtin_amdgcn_exp2f(m - mn);
;                     l *= alpha;
; #pragma unroll
;                     for (int db = 0; db < DVB; ++db)
; #pragma unroll
;                         for (int i = 0; i < 16; ++i) o[db][i] *= alpha;
;                     m = mn;
.LBB0_1268:
	s_or_b64 exec, exec, s[8:9]
	v_max_f32_e32 v2, v130, v131
	v_max3_f32 v2, v2, v132, v133
	v_max3_f32 v2, v2, v134, v135
	v_max3_f32 v2, v2, v136, v137
	v_max3_f32 v2, v2, v138, v139
	v_max3_f32 v2, v2, v140, v141
	v_max3_f32 v2, v2, v142, v143
	v_max3_f32 v2, v2, v144, v145
	v_max3_f32 v2, v2, v114, v115
	v_max3_f32 v2, v2, v116, v117
	v_max3_f32 v2, v2, v118, v119
	v_max3_f32 v2, v2, v120, v121
	v_max3_f32 v2, v2, v122, v123
	v_max3_f32 v2, v2, v124, v125
	v_max3_f32 v2, v2, v126, v127
	v_max3_f32 v2, v2, v128, v129
	v_mov_b32_e32 v4, v2
	s_nop 1
	v_permlane32_swap_b32_e32 v2, v4
	v_max_f32_e32 v198, v2, v4
	v_pk_add_f32 v[4:5], v[206:207], v[198:199]
	s_nop 0
	v_cvt_pk_bf16_f32 v2, v4, 0
	v_lshlrev_b32_e32 v2, 16, v2
	v_cmp_gt_f32_e64 s[8:9], v4, v5
	s_nop 1
	v_cndmask_b32_e64 v4, v207, v2, s[8:9]
	v_sub_f32_e32 v2, v4, v206
	v_cmp_neq_f32_e32 vcc, 0, v2
	s_cbranch_vccz .LBB0_1273
	v_cndmask_b32_e64 v5, 0, 1, s[8:9]
	v_cmp_ne_u32_e32 vcc, 0, v5
	s_cbranch_vccz .LBB0_1271
	v_sub_f32_e32 v5, v207, v4
	v_exp_f32_e32 v8, v5
	s_nop 0
	v_mul_f32_e32 v6, v6, v8
	v_pk_mul_f32 v[112:113], v[112:113], v[8:9] op_sel_hi:[1,0]
	v_pk_mul_f32 v[110:111], v[110:111], v[8:9] op_sel_hi:[1,0]
	v_pk_mul_f32 v[108:109], v[108:109], v[8:9] op_sel_hi:[1,0]
	v_pk_mul_f32 v[106:107], v[106:107], v[8:9] op_sel_hi:[1,0]
	v_pk_mul_f32 v[104:105], v[104:105], v[8:9] op_sel_hi:[1,0]
	v_pk_mul_f32 v[102:103], v[102:103], v[8:9] op_sel_hi:[1,0]
	v_pk_mul_f32 v[100:101], v[100:101], v[8:9] op_sel_hi:[1,0]
	v_pk_mul_f32 v[98:99], v[98:99], v[8:9] op_sel_hi:[1,0]
	v_pk_mul_f32 v[96:97], v[96:97], v[8:9] op_sel_hi:[1,0]
	v_pk_mul_f32 v[94:95], v[94:95], v[8:9] op_sel_hi:[1,0]
	v_pk_mul_f32 v[92:93], v[92:93], v[8:9] op_sel_hi:[1,0]
	v_pk_mul_f32 v[90:91], v[90:91], v[8:9] op_sel_hi:[1,0]
	v_pk_mul_f32 v[88:89], v[88:89], v[8:9] op_sel_hi:[1,0]
	v_pk_mul_f32 v[86:87], v[86:87], v[8:9] op_sel_hi:[1,0]
	v_pk_mul_f32 v[84:85], v[84:85], v[8:9] op_sel_hi:[1,0]
	v_pk_mul_f32 v[82:83], v[82:83], v[8:9] op_sel_hi:[1,0]
	v_pk_mul_f32 v[80:81], v[80:81], v[8:9] op_sel_hi:[1,0]
	v_pk_mul_f32 v[78:79], v[78:79], v[8:9] op_sel_hi:[1,0]
	v_pk_mul_f32 v[76:77], v[76:77], v[8:9] op_sel_hi:[1,0]
	v_pk_mul_f32 v[74:75], v[74:75], v[8:9] op_sel_hi:[1,0]
	v_pk_mul_f32 v[72:73], v[72:73], v[8:9] op_sel_hi:[1,0]
	v_pk_mul_f32 v[70:71], v[70:71], v[8:9] op_sel_hi:[1,0]
	v_pk_mul_f32 v[68:69], v[68:69], v[8:9] op_sel_hi:[1,0]
	v_pk_mul_f32 v[66:67], v[66:67], v[8:9] op_sel_hi:[1,0]
	v_pk_mul_f32 v[64:65], v[64:65], v[8:9] op_sel_hi:[1,0]
	v_pk_mul_f32 v[62:63], v[62:63], v[8:9] op_sel_hi:[1,0]
	v_pk_mul_f32 v[60:61], v[60:61], v[8:9] op_sel_hi:[1,0]
	v_pk_mul_f32 v[58:59], v[58:59], v[8:9] op_sel_hi:[1,0]
	v_pk_mul_f32 v[56:57], v[56:57], v[8:9] op_sel_hi:[1,0]
	v_pk_mul_f32 v[54:55], v[54:55], v[8:9] op_sel_hi:[1,0]
	v_pk_mul_f32 v[52:53], v[52:53], v[8:9] op_sel_hi:[1,0]
	v_pk_mul_f32 v[50:51], v[50:51], v[8:9] op_sel_hi:[1,0]
	s_branch .LBB0_1272

; DI unsigned pk_bf16(float a, float b) { f32x2 v = {a, b}; bf2_t r = __builtin_convertvector(v, bf2_t); return __builtin_bit_cast(unsigned, r); }
; DI float xhalf_max(float v) { const auto r = __builtin_amdgcn_permlane32_swap(__float_as_uint(v), __float_as_uint(v), false, false); return fmaxf(__uint_as_float(r[0]), __uint_as_float(r[1])); }
;     ...
;             float mx = s[0][0];
; #pragma unroll
;             for (int i = 1; i < 16; ++i) mx = fmaxf(mx, s[0][i]);
; #pragma unroll
;             for (int i = 0; i < 16; ++i) mx = fmaxf(mx, s[1][i]);
;             mx = xhalf_max(mx);
;             const float mabs = mi + mx;
;             const bool up = mabs > m + 8.0f;
;             const float mn = up ? __uint_as_float(pk_bf16(mabs, 0.f) << 16) : m;
;             const float shift = mn - mi;
;             if (__ballot(shift != 0.f) != 0) {
;                 if (__ballot(up) != 0) {
;                     const float alpha = __builtin_amdgcn_exp2f(m - mn);
;                     l *= alpha;
; #pragma unroll
;                     for (int db = 0; db < DVB; ++db)
; #pragma unroll
;                         for (int i = 0; i < 16; ++i) o[db][i] *= alpha;
;                     m = mn;
.LBB0_1286:
	s_or_b64 exec, exec, s[52:53]
	v_max_f32_e32 v2, v34, v35
	v_max3_f32 v2, v2, v36, v37
	v_max3_f32 v2, v2, v38, v39
	v_max3_f32 v2, v2, v40, v41
	v_max3_f32 v2, v2, v42, v43
	v_max3_f32 v2, v2, v44, v45
	v_max3_f32 v2, v2, v46, v47
	v_max3_f32 v2, v2, v48, v49
	v_max3_f32 v2, v2, v18, v19
	v_max3_f32 v2, v2, v20, v21
	v_max3_f32 v2, v2, v22, v23
	v_max3_f32 v2, v2, v24, v25
	v_max3_f32 v2, v2, v26, v27
	v_max3_f32 v2, v2, v28, v29
	v_max3_f32 v2, v2, v30, v31
	v_max3_f32 v2, v2, v32, v33
	v_mov_b32_e32 v4, v2
	s_nop 1
	v_permlane32_swap_b32_e32 v2, v4
	v_max_f32_e32 v198, v2, v4
	v_mov_b32_e32 v209, v207
	v_pk_add_f32 v[4:5], v[208:209], v[198:199]
	s_nop 0
	v_cvt_pk_bf16_f32 v2, v4, 0
	v_lshlrev_b32_e32 v2, 16, v2
	v_cmp_gt_f32_e64 s[8:9], v4, v5
	s_nop 1
	v_cndmask_b32_e64 v4, v207, v2, s[8:9]
	v_sub_f32_e32 v2, v4, v208
	v_cmp_neq_f32_e32 vcc, 0, v2
	s_cbranch_vccz .LBB0_1291
	v_cndmask_b32_e64 v5, 0, 1, s[8:9]
	v_cmp_ne_u32_e32 vcc, 0, v5
	s_cbranch_vccz .LBB0_1289
	v_sub_f32_e32 v5, v207, v4
	v_exp_f32_e32 v8, v5
	s_nop 0
	v_mul_f32_e32 v6, v6, v8
	v_pk_mul_f32 v[112:113], v[112:113], v[8:9] op_sel_hi:[1,0]
	v_pk_mul_f32 v[110:111], v[110:111], v[8:9] op_sel_hi:[1,0]
	v_pk_mul_f32 v[108:109], v[108:109], v[8:9] op_sel_hi:[1,0]
	v_pk_mul_f32 v[106:107], v[106:107], v[8:9] op_sel_hi:[1,0]
	v_pk_mul_f32 v[104:105], v[104:105], v[8:9] op_sel_hi:[1,0]
	v_pk_mul_f32 v[102:103], v[102:103], v[8:9] op_sel_hi:[1,0]
	v_pk_mul_f32 v[100:101], v[100:101], v[8:9] op_sel_hi:[1,0]
	v_pk_mul_f32 v[98:99], v[98:99], v[8:9] op_sel_hi:[1,0]
	v_pk_mul_f32 v[96:97], v[96:97], v[8:9] op_sel_hi:[1,0]
	v_pk_mul_f32 v[94:95], v[94:95], v[8:9] op_sel_hi:[1,0]
	v_pk_mul_f32 v[92:93], v[92:93], v[8:9] op_sel_hi:[1,0]
	v_pk_mul_f32 v[90:91], v[90:91], v[8:9] op_sel_hi:[1,0]
	v_pk_mul_f32 v[88:89], v[88:89], v[8:9] op_sel_hi:[1,0]
	v_pk_mul_f32 v[86:87], v[86:87], v[8:9] op_sel_hi:[1,0]
	v_pk_mul_f32 v[84:85], v[84:85], v[8:9] op_sel_hi:[1,0]
	v_pk_mul_f32 v[82:83], v[82:83], v[8:9] op_sel_hi:[1,0]
	v_pk_mul_f32 v[80:81], v[80:81], v[8:9] op_sel_hi:[1,0]
	v_pk_mul_f32 v[78:79], v[78:79], v[8:9] op_sel_hi:[1,0]
	v_pk_mul_f32 v[76:77], v[76:77], v[8:9] op_sel_hi:[1,0]
	v_pk_mul_f32 v[74:75], v[74:75], v[8:9] op_sel_hi:[1,0]
	v_pk_mul_f32 v[72:73], v[72:73], v[8:9] op_sel_hi:[1,0]
	v_pk_mul_f32 v[70:71], v[70:71], v[8:9] op_sel_hi:[1,0]
	v_pk_mul_f32 v[68:69], v[68:69], v[8:9] op_sel_hi:[1,0]
	v_pk_mul_f32 v[66:67], v[66:67], v[8:9] op_sel_hi:[1,0]
	v_pk_mul_f32 v[64:65], v[64:65], v[8:9] op_sel_hi:[1,0]
	v_pk_mul_f32 v[62:63], v[62:63], v[8:9] op_sel_hi:[1,0]
	v_pk_mul_f32 v[60:61], v[60:61], v[8:9] op_sel_hi:[1,0]
	v_pk_mul_f32 v[58:59], v[58:59], v[8:9] op_sel_hi:[1,0]
	v_pk_mul_f32 v[56:57], v[56:57], v[8:9] op_sel_hi:[1,0]
	v_pk_mul_f32 v[54:55], v[54:55], v[8:9] op_sel_hi:[1,0]
	v_pk_mul_f32 v[52:53], v[52:53], v[8:9] op_sel_hi:[1,0]
	v_pk_mul_f32 v[50:51], v[50:51], v[8:9] op_sel_hi:[1,0]
	s_branch .LBB0_1290

; DI unsigned pk_bf16(float a, float b) { f32x2 v = {a, b}; bf2_t r = __builtin_convertvector(v, bf2_t); return __builtin_bit_cast(unsigned, r); }
; DI float xhalf_max(float v) { const auto r = __builtin_amdgcn_permlane32_swap(__float_as_uint(v), __float_as_uint(v), false, false); return fmaxf(__uint_as_float(r[0]), __uint_as_float(r[1])); }
;     ...
;             float mx = s[0][0];
; #pragma unroll
;             for (int i = 1; i < 16; ++i) mx = fmaxf(mx, s[0][i]);
; #pragma unroll
;             for (int i = 0; i < 16; ++i) mx = fmaxf(mx, s[1][i]);
;             mx = xhalf_max(mx);
;             const float mabs = mi + mx;
;             const bool up = mabs > m + 8.0f;
;             const float mn = up ? __uint_as_float(pk_bf16(mabs, 0.f) << 16) : m;
;             const float shift = mn - mi;
;             if (__ballot(shift != 0.f) != 0) {
;                 if (__ballot(up) != 0) {
;                     const float alpha = __builtin_amdgcn_exp2f(m - mn);
;                     l *= alpha;
; #pragma unroll
;                     for (int db = 0; db < DVB; ++db)
; #pragma unroll
;                         for (int i = 0; i < 16; ++i) o[db][i] *= alpha;
;                     m = mn;
.LBB0_1361:
	s_or_b64 exec, exec, s[8:9]
	v_max_f32_e32 v2, v18, v19
	v_max3_f32 v2, v2, v20, v21
	v_max3_f32 v2, v2, v22, v23
	v_max3_f32 v2, v2, v24, v25
	v_max3_f32 v2, v2, v26, v27
	v_max3_f32 v2, v2, v28, v29
	v_max3_f32 v2, v2, v30, v31
	v_max3_f32 v2, v2, v32, v33
	v_max3_f32 v2, v2, v34, v35
	v_max3_f32 v2, v2, v16, v17
	v_max3_f32 v2, v2, v14, v15
	v_max3_f32 v2, v2, v12, v13
	v_max3_f32 v2, v2, v10, v11
	v_max3_f32 v2, v2, v6, v7
	v_max3_f32 v2, v2, v8, v9
	v_max3_f32 v2, v2, v4, v5
	v_mov_b32_e32 v36, v2
	s_nop 1
	v_permlane32_swap_b32_e32 v2, v36
	v_max_f32_e32 v158, v2, v36
	v_pk_add_f32 v[36:37], v[166:167], v[158:159]
	s_nop 0
	v_cvt_pk_bf16_f32 v2, v36, 0
	v_lshlrev_b32_e32 v2, 16, v2
	v_cmp_gt_f32_e64 s[8:9], v36, v37
	s_nop 1
	v_cndmask_b32_e64 v36, v167, v2, s[8:9]
	v_sub_f32_e32 v2, v36, v166
	v_cmp_neq_f32_e32 vcc, 0, v2
	s_cbranch_vccz .LBB0_1366
	v_cndmask_b32_e64 v37, 0, 1, s[8:9]
	v_cmp_ne_u32_e32 vcc, 0, v37
	s_cbranch_vccz .LBB0_1364
	v_sub_f32_e32 v37, v167, v36
	v_exp_f32_e32 v38, v37
	s_nop 0
	v_mul_f32_e32 v192, v192, v38
	v_pk_mul_f32 v[96:97], v[96:97], v[38:39] op_sel_hi:[1,0]
	v_pk_mul_f32 v[94:95], v[94:95], v[38:39] op_sel_hi:[1,0]
	v_pk_mul_f32 v[92:93], v[92:93], v[38:39] op_sel_hi:[1,0]
	v_pk_mul_f32 v[90:91], v[90:91], v[38:39] op_sel_hi:[1,0]
	v_pk_mul_f32 v[88:89], v[88:89], v[38:39] op_sel_hi:[1,0]
	v_pk_mul_f32 v[86:87], v[86:87], v[38:39] op_sel_hi:[1,0]
	v_pk_mul_f32 v[84:85], v[84:85], v[38:39] op_sel_hi:[1,0]
	v_pk_mul_f32 v[82:83], v[82:83], v[38:39] op_sel_hi:[1,0]
	v_pk_mul_f32 v[80:81], v[80:81], v[38:39] op_sel_hi:[1,0]
	v_pk_mul_f32 v[78:79], v[78:79], v[38:39] op_sel_hi:[1,0]
	v_pk_mul_f32 v[76:77], v[76:77], v[38:39] op_sel_hi:[1,0]
	v_pk_mul_f32 v[74:75], v[74:75], v[38:39] op_sel_hi:[1,0]
	v_pk_mul_f32 v[72:73], v[72:73], v[38:39] op_sel_hi:[1,0]
	v_pk_mul_f32 v[70:71], v[70:71], v[38:39] op_sel_hi:[1,0]
	v_pk_mul_f32 v[68:69], v[68:69], v[38:39] op_sel_hi:[1,0]
	v_pk_mul_f32 v[66:67], v[66:67], v[38:39] op_sel_hi:[1,0]
	s_branch .LBB0_1365

; DI unsigned pk_bf16(float a, float b) { f32x2 v = {a, b}; bf2_t r = __builtin_convertvector(v, bf2_t); return __builtin_bit_cast(unsigned, r); }
; DI float xhalf_max(float v) { const auto r = __builtin_amdgcn_permlane32_swap(__float_as_uint(v), __float_as_uint(v), false, false); return fmaxf(__uint_as_float(r[0]), __uint_as_float(r[1])); }
;     ...
;             float mx = s[0][0];
; #pragma unroll
;             for (int i = 1; i < 16; ++i) mx = fmaxf(mx, s[0][i]);
; #pragma unroll
;             for (int i = 0; i < 16; ++i) mx = fmaxf(mx, s[1][i]);
;             mx = xhalf_max(mx);
;             const float mabs = mi + mx;
;             const bool up = mabs > m + 8.0f;
;             const float mn = up ? __uint_as_float(pk_bf16(mabs, 0.f) << 16) : m;
;             const float shift = mn - mi;
;             if (__ballot(shift != 0.f) != 0) {
;                 if (__ballot(up) != 0) {
;                     const float alpha = __builtin_amdgcn_exp2f(m - mn);
;                     l *= alpha;
; #pragma unroll
;                     for (int db = 0; db < DVB; ++db)
; #pragma unroll
;                         for (int i = 0; i < 16; ++i) o[db][i] *= alpha;
;                     m = mn;
.LBB0_1382:
	s_or_b64 exec, exec, s[6:7]
	v_max_f32_e32 v2, v50, v51
	v_max3_f32 v2, v2, v52, v53
	v_max3_f32 v2, v2, v54, v55
	v_max3_f32 v2, v2, v56, v57
	v_max3_f32 v2, v2, v58, v59
	v_max3_f32 v2, v2, v60, v61
	v_max3_f32 v2, v2, v62, v63
	v_max3_f32 v2, v2, v64, v65
	v_max3_f32 v2, v2, v98, v99
	v_max3_f32 v2, v2, v16, v17
	v_max3_f32 v2, v2, v14, v15
	v_max3_f32 v2, v2, v12, v13
	v_max3_f32 v2, v2, v10, v11
	v_max3_f32 v2, v2, v8, v9
	v_max3_f32 v2, v2, v6, v7
	v_max3_f32 v2, v2, v4, v5
	v_mov_b32_e32 v100, v2
	s_nop 1
	v_permlane32_swap_b32_e32 v2, v100
	v_max_f32_e32 v158, v2, v100
	v_mov_b32_e32 v169, v167
	v_pk_add_f32 v[100:101], v[168:169], v[158:159]
	s_nop 0
	v_cvt_pk_bf16_f32 v2, v100, 0
	v_lshlrev_b32_e32 v2, 16, v2
	v_cmp_gt_f32_e64 s[6:7], v100, v101
	s_nop 1
	v_cndmask_b32_e64 v100, v167, v2, s[6:7]
	v_sub_f32_e32 v2, v100, v168
	v_cmp_neq_f32_e32 vcc, 0, v2
	s_cbranch_vccz .LBB0_1387
	v_cndmask_b32_e64 v101, 0, 1, s[6:7]
	v_cmp_ne_u32_e32 vcc, 0, v101
	s_cbranch_vccz .LBB0_1385
	v_sub_f32_e32 v101, v167, v100
	v_exp_f32_e32 v102, v101
	s_nop 0
	v_mul_f32_e32 v192, v192, v102
	v_pk_mul_f32 v[96:97], v[96:97], v[102:103] op_sel_hi:[1,0]
	v_pk_mul_f32 v[94:95], v[94:95], v[102:103] op_sel_hi:[1,0]
	v_pk_mul_f32 v[92:93], v[92:93], v[102:103] op_sel_hi:[1,0]
	v_pk_mul_f32 v[90:91], v[90:91], v[102:103] op_sel_hi:[1,0]
	v_pk_mul_f32 v[88:89], v[88:89], v[102:103] op_sel_hi:[1,0]
	v_pk_mul_f32 v[86:87], v[86:87], v[102:103] op_sel_hi:[1,0]
	v_pk_mul_f32 v[84:85], v[84:85], v[102:103] op_sel_hi:[1,0]
	v_pk_mul_f32 v[82:83], v[82:83], v[102:103] op_sel_hi:[1,0]
	v_pk_mul_f32 v[80:81], v[80:81], v[102:103] op_sel_hi:[1,0]
	v_pk_mul_f32 v[78:79], v[78:79], v[102:103] op_sel_hi:[1,0]
	v_pk_mul_f32 v[76:77], v[76:77], v[102:103] op_sel_hi:[1,0]
	v_pk_mul_f32 v[74:75], v[74:75], v[102:103] op_sel_hi:[1,0]
	v_pk_mul_f32 v[72:73], v[72:73], v[102:103] op_sel_hi:[1,0]
	v_pk_mul_f32 v[70:71], v[70:71], v[102:103] op_sel_hi:[1,0]
	v_pk_mul_f32 v[68:69], v[68:69], v[102:103] op_sel_hi:[1,0]
	v_pk_mul_f32 v[66:67], v[66:67], v[102:103] op_sel_hi:[1,0]
	s_branch .LBB0_1386

; #define MFMA32(a, b, c) __builtin_amdgcn_mfma_f32_32x32x16_bf16((a), (b), (c), 0, 0, 0)
; DI float xhalf_sum(float v) { const auto r = __builtin_amdgcn_permlane32_swap(__float_as_uint(v), __float_as_uint(v), false, false); return __uint_as_float(r[0]) + __uint_as_float(r[1]); }
; DI void phase_index(const Params& p, unsigned char* lds) {
;     ...
;         auto mma = [&](f32x16& s, unsigned off) {
; #pragma unroll
;             for (int i = 0; i < 16; ++i) s[i] = 0.f;
; #pragma unroll
;             for (int ks = 0; ks < 4; ++ks) { const bf16x8 kf = *(const bf16x8*)(lds + off + ks * 32); s = MFMA32(qf[ks], kf, s); }
;         };
;         auto proc = [&](auto PASSC, auto DIAGC, const f32x16& s, int k0, int kb) {
;             constexpr int PASS = decltype(PASSC)::value; constexpr bool DIAG = decltype(DIAGC)::value != 0;
;             f32x4 tot;
; #pragma unroll
;             for (int q = 0; q < 4; ++q) {
;                 float pr = 0.f;
; #pragma unroll
;                 for (int e = 0; e < 4; ++e) pr += wq[q][e] * fmaxf(s[4 * q + e], 0.f);
;                 tot[q] = xhalf_sum(pr);
;             }
;             const int key = k0 + 32 * kb + r32;
; #pragma unroll
;             for (int qq = 0; qq < 2; ++qq) {
;                 const float t_lo = tot[qq], t_hi = tot[2 + qq];
;                 const float sc = ((lane & 32) ? t_hi : t_lo) + 0.0f;
;                 const unsigned ub = __float_as_uint(sc);
;                 const unsigned uk = ub ^ ((unsigned)((int)ub >> 31) | 0x80000000u);
;                 const bool valid = DIAG ? (key <= tq0 + qq) : true;
;                 if (PASS == 0) {
;                     if (valid) { const unsigned a = (uk >> 21) & 0x7feu; atomicAdd((unsigned*)(lds + hbase0 + qq * 2048 + (a & ~3u)), 1u << ((a & 2u) << 3)); }
.LBB0_2567:
	s_bitcmp1_b32 s28, 0
	s_cselect_b32 s34, 0x9000, 0
	v_add_u32_e32 v106, s34, v154
	ds_read_b128 v[2:5], v106
	ds_read_b128 v[6:9], v106 offset:32
	s_cmp_lg_u32 s0, 0
	s_cselect_b64 s[28:29], -1, 0
	s_and_b64 vcc, exec, s[28:29]
	s_waitcnt lgkmcnt(1)
	v_mfma_f32_32x32x16_bf16 v[18:33], v[42:45], v[2:5], 0
	ds_read_b128 v[2:5], v106 offset:64
	ds_read_b128 v[102:105], v106 offset:96
	s_waitcnt lgkmcnt(2)
	v_mfma_f32_32x32x16_bf16 v[18:33], v[34:37], v[6:9], v[18:33]
	s_waitcnt lgkmcnt(1)
	v_mfma_f32_32x32x16_bf16 v[18:33], v[38:41], v[2:5], v[18:33]
	ds_read_b128 v[2:5], v106 offset:4608
	ds_read_b128 v[108:111], v106 offset:4640
	s_waitcnt lgkmcnt(2)
	v_mfma_f32_32x32x16_bf16 v[18:33], v[46:49], v[102:105], v[18:33]
	s_waitcnt lgkmcnt(1)
	v_mfma_f32_32x32x16_bf16 v[2:17], v[42:45], v[2:5], 0
	s_nop 9
	v_max_f32_e32 v18, 0, v18
	v_max_f32_e32 v103, 0, v21
	v_max_f32_e32 v21, 0, v22
	v_max_f32_e32 v102, 0, v20
	v_max_f32_e32 v22, 0, v23
	v_fma_f32 v20, v50, v18, 0
	v_fma_f32 v18, v54, v21, 0
	s_waitcnt lgkmcnt(0)
	v_mfma_f32_32x32x16_bf16 v[2:17], v[34:37], v[108:111], v[2:17]
	v_max_f32_e32 v23, 0, v24
	v_fmac_f32_e32 v18, v55, v22
	v_max_f32_e32 v24, 0, v25
	v_max_f32_e32 v25, 0, v26
	v_fmac_f32_e32 v18, v56, v23
	v_fma_f32 v21, v58, v25, 0
	v_fmac_f32_e32 v18, v57, v24
	ds_read_b128 v[22:25], v106 offset:4672
	v_max_f32_e32 v19, 0, v19
	v_max_f32_e32 v26, 0, v27
	v_max_f32_e32 v27, 0, v28
	v_fmac_f32_e32 v20, v51, v19
	v_fmac_f32_e32 v21, v59, v26
	v_fmac_f32_e32 v21, v60, v27
	v_max_f32_e32 v19, 0, v29
	v_fmac_f32_e32 v21, v61, v19
	v_max_f32_e32 v19, v30, v30
	v_max_f32_e32 v30, 0, v31
	ds_read_b128 v[26:29], v106 offset:4704
	s_waitcnt lgkmcnt(1)
	v_mfma_f32_32x32x16_bf16 v[2:17], v[38:41], v[22:25], v[2:17]
	v_max_f32_e32 v19, 0, v19
	v_fma_f32 v19, v62, v19, 0
	v_fmac_f32_e32 v19, v63, v30
	v_max_f32_e32 v22, 0, v32
	v_fmac_f32_e32 v19, v64, v22
	s_waitcnt lgkmcnt(0)
	v_mfma_f32_32x32x16_bf16 v[2:17], v[46:49], v[26:29], v[2:17]
	v_fmac_f32_e32 v20, v52, v102
	v_max_f32_e32 v22, 0, v33
	v_fmac_f32_e32 v20, v53, v103
	v_fmac_f32_e32 v19, v65, v22
	s_cbranch_vccz .LBB0_2575
	v_mov_b32_e32 v22, v20
	v_mov_b32_e32 v23, v20
	s_nop 1
	v_permlane32_swap_b32_e32 v22, v23
	v_add_f32_e32 v22, v22, v23
	v_mov_b32_e32 v23, v18
	v_mov_b32_e32 v24, v18
	s_nop 1
	v_permlane32_swap_b32_e32 v23, v24
	v_add_f32_e32 v23, v23, v24
	v_mov_b32_e32 v24, v21
	v_mov_b32_e32 v25, v21
	s_nop 1
	v_permlane32_swap_b32_e32 v24, v25
	v_add_f32_e32 v24, v24, v25
	v_cndmask_b32_e64 v22, v24, v22, s[4:5]
	v_add_f32_e32 v22, 0, v22
	v_ashrrev_i32_e32 v24, 31, v22
	v_bitop3_b32 v22, v24, v22, s82 bitop3:0x36
	v_lshrrev_b32_e32 v24, 21, v22
	v_lshrrev_b32_e32 v22, 18, v22
	v_and_b32_e32 v24, 0x7fc, v24
	v_and_b32_e32 v22, 16, v22
	v_add_u32_e32 v24, v123, v24
	v_lshlrev_b32_e64 v22, v22, 1
	ds_add_u32 v24, v22
	v_mov_b32_e32 v25, v19
	v_mov_b32_e32 v26, v19
	s_nop 1
	v_permlane32_swap_b32_e32 v25, v26
	v_add_f32_e32 v22, v25, v26
	v_cndmask_b32_e64 v22, v22, v23, s[4:5]
	s_mov_b64 s[30:31], -1
	s_cbranch_execz .LBB0_2576
	s_and_saveexec_b64 s[50:51], s[30:31]
	s_cbranch_execz .LBB0_2571

; #define MFMA32(a, b, c) __builtin_amdgcn_mfma_f32_32x32x16_bf16((a), (b), (c), 0, 0, 0)
; DI float xhalf_sum(float v) { const auto r = __builtin_amdgcn_permlane32_swap(__float_as_uint(v), __float_as_uint(v), false, false); return __uint_as_float(r[0]) + __uint_as_float(r[1]); }
; DI void phase_index(const Params& p, unsigned char* lds) {
;     ...
;         auto mma = [&](f32x16& s, unsigned off) {
; #pragma unroll
;             for (int i = 0; i < 16; ++i) s[i] = 0.f;
; #pragma unroll
;             for (int ks = 0; ks < 4; ++ks) { const bf16x8 kf = *(const bf16x8*)(lds + off + ks * 32); s = MFMA32(qf[ks], kf, s); }
;         };
;         auto proc = [&](auto PASSC, auto DIAGC, const f32x16& s, int k0, int kb) {
;             constexpr int PASS = decltype(PASSC)::value; constexpr bool DIAG = decltype(DIAGC)::value != 0;
;             f32x4 tot;
; #pragma unroll
;             for (int q = 0; q < 4; ++q) {
;                 float pr = 0.f;
; #pragma unroll
;                 for (int e = 0; e < 4; ++e) pr += wq[q][e] * fmaxf(s[4 * q + e], 0.f);
;                 tot[q] = xhalf_sum(pr);
.LBB0_2635:
	v_add_u32_e32 v168, s1, v163
	v_add_u32_e32 v18, 0x11200, v168
	ds_read_b128 v[18:21], v18
	v_add_u32_e32 v22, 0x11220, v168
	ds_read_b128 v[172:175], v22
	v_add_u32_e32 v177, 0x11240, v168
	s_waitcnt lgkmcnt(1)
	v_mfma_f32_32x32x16_bf16 v[18:33], v[42:45], v[18:21], 0
	v_max_f32_e32 v180, v6, v6
	v_max_f32_e32 v181, v7, v7
	v_max_f32_e32 v167, 0, v2
	v_max_f32_e32 v182, 0, v4
	v_max_f32_e32 v170, 0, v180
	v_fma_f32 v170, v54, v170, 0
	s_waitcnt lgkmcnt(0)
	v_mfma_f32_32x32x16_bf16 v[18:33], v[34:37], v[172:175], v[18:33]
	ds_read_b128 v[172:175], v177
	v_add_u32_e32 v178, 0x11260, v168
	v_max_f32_e32 v183, 0, v5
	ds_read_b128 v[176:179], v178
	v_max_f32_e32 v169, 0, v3
	s_waitcnt lgkmcnt(1)
	v_mfma_f32_32x32x16_bf16 v[18:33], v[38:41], v[172:175], v[18:33]
	v_max_f32_e32 v172, 0, v181
	v_fma_f32 v173, v50, v167, 0
	v_fmac_f32_e32 v170, v55, v172
	v_max_f32_e32 v167, 0, v8
	v_fmac_f32_e32 v170, v56, v167
	v_max_f32_e32 v167, 0, v9
	v_fmac_f32_e32 v170, v57, v167
	v_max_f32_e32 v167, 0, v10
	v_fma_f32 v174, v58, v167, 0
	v_max_f32_e32 v167, 0, v11
	v_fmac_f32_e32 v174, v59, v167
	v_max_f32_e32 v167, 0, v12
	v_fmac_f32_e32 v174, v60, v167
	v_max_f32_e32 v167, 0, v13
	v_fmac_f32_e32 v174, v61, v167
	s_waitcnt lgkmcnt(0)
	v_mfma_f32_32x32x16_bf16 v[18:33], v[46:49], v[176:179], v[18:33]
	v_max_f32_e32 v167, 0, v14
	v_fma_f32 v172, v62, v167, 0
	v_max_f32_e32 v167, 0, v15
	v_fmac_f32_e32 v172, v63, v167
	v_max_f32_e32 v167, 0, v16
	s_cmp_lg_u32 s52, s55
	v_fmac_f32_e32 v173, v51, v169
	v_fmac_f32_e32 v172, v64, v167
	s_cselect_b64 s[28:29], -1, 0
	v_fmac_f32_e32 v173, v52, v182
	v_max_f32_e32 v167, 0, v17
	v_fmac_f32_e32 v173, v53, v183
	v_fmac_f32_e32 v172, v65, v167
	s_mov_b64 s[30:31], -1
	s_and_b64 vcc, exec, s[28:29]
	s_cbranch_vccnz .LBB0_2669
	s_and_b64 vcc, exec, s[30:31]
	s_cbranch_vccnz .LBB0_2682

; DI float xhalf_sum(float v) { const auto r = __builtin_amdgcn_permlane32_swap(__float_as_uint(v), __float_as_uint(v), false, false); return __uint_as_float(r[0]) + __uint_as_float(r[1]); }
; DI void phase_index(const Params& p, unsigned char* lds) {
;     ...
;         auto proc = [&](auto PASSC, auto DIAGC, const f32x16& s, int k0, int kb) {
;             constexpr int PASS = decltype(PASSC)::value; constexpr bool DIAG = decltype(DIAGC)::value != 0;
;             f32x4 tot;
; #pragma unroll
;             for (int q = 0; q < 4; ++q) {
;                 float pr = 0.f;
; #pragma unroll
;                 for (int e = 0; e < 4; ++e) pr += wq[q][e] * fmaxf(s[4 * q + e], 0.f);
;                 tot[q] = xhalf_sum(pr);
;             }
;             const int key = k0 + 32 * kb + r32;
; #pragma unroll
;             for (int qq = 0; qq < 2; ++qq) {
;                 const float t_lo = tot[qq], t_hi = tot[2 + qq];
;                 const float sc = ((lane & 32) ? t_hi : t_lo) + 0.0f;
;                 const unsigned ub = __float_as_uint(sc);
;                 const unsigned uk = ub ^ ((unsigned)((int)ub >> 31) | 0x80000000u);
;                 const bool valid = DIAG ? (key <= tq0 + qq) : true;
;                 if (PASS == 0) {
;                     if (valid) { const unsigned a = (uk >> 21) & 0x7feu; atomicAdd((unsigned*)(lds + hbase0 + qq * 2048 + (a & ~3u)), 1u << ((a & 2u) << 3)); }
;                 } else if (PASS == 1) {
;                     if (valid && (int)(uk >> 22) == b1v[qq]) { const unsigned a = (uk >> 11) & 0x7feu; atomicAdd((unsigned*)(lds + hbase0 + qq * 2048 + (a & ~3u)), 1u << ((a & 2u) << 3)); }
.LBB0_3242:
	v_add_u32_e32 v115, s50, v113
	v_add_u32_e32 v18, 0x11200, v115
	ds_read_b128 v[18:21], v18
	v_add_u32_e32 v22, 0x11220, v115
	ds_read_b128 v[162:165], v22
	v_add_u32_e32 v167, 0x11240, v115
	s_waitcnt lgkmcnt(1)
	v_mfma_f32_32x32x16_bf16 v[18:33], v[42:45], v[18:21], 0
	v_max_f32_e32 v116, 0, v2
	v_max_f32_e32 v170, v6, v6
	v_max_f32_e32 v173, 0, v3
	v_fma_f32 v117, v50, v116, 0
	v_max_f32_e32 v172, v7, v7
	s_waitcnt lgkmcnt(0)
	v_mfma_f32_32x32x16_bf16 v[18:33], v[34:37], v[162:165], v[18:33]
	ds_read_b128 v[162:165], v167
	v_max_f32_e32 v161, 0, v4
	v_fmac_f32_e32 v117, v51, v173
	v_fmac_f32_e32 v117, v52, v161
	v_max_f32_e32 v161, 0, v8
	s_waitcnt lgkmcnt(0)
	v_mfma_f32_32x32x16_bf16 v[18:33], v[38:41], v[162:165], v[18:33]
	v_max_f32_e32 v162, 0, v170
	v_max_f32_e32 v163, 0, v172
	v_fma_f32 v116, v54, v162, 0
	v_fmac_f32_e32 v116, v55, v163
	v_fmac_f32_e32 v116, v56, v161
	v_max_f32_e32 v161, 0, v9
	v_fmac_f32_e32 v116, v57, v161
	v_max_f32_e32 v161, 0, v10
	v_add_u32_e32 v168, 0x11260, v115
	v_fma_f32 v162, v58, v161, 0
	v_max_f32_e32 v174, 0, v5
	ds_read_b128 v[166:169], v168
	v_max_f32_e32 v161, 0, v11
	v_fmac_f32_e32 v162, v59, v161
	v_max_f32_e32 v161, 0, v12
	v_fmac_f32_e32 v162, v60, v161
	v_max_f32_e32 v161, 0, v13
	s_waitcnt lgkmcnt(0)
	v_mfma_f32_32x32x16_bf16 v[18:33], v[46:49], v[166:169], v[18:33]
	v_fmac_f32_e32 v162, v61, v161
	v_max_f32_e32 v161, 0, v14
	v_fma_f32 v161, v62, v161, 0
	v_max_f32_e32 v163, 0, v15
	v_fmac_f32_e32 v161, v63, v163
	v_max_f32_e32 v163, 0, v16
	s_cmp_lg_u32 s0, s51
	v_fmac_f32_e32 v161, v64, v163
	s_cselect_b64 s[30:31], -1, 0
	v_max_f32_e32 v163, 0, v17
	v_fmac_f32_e32 v117, v53, v174
	v_fmac_f32_e32 v161, v65, v163
	s_and_b64 vcc, exec, s[30:31]
	s_cbranch_vccz .LBB0_3246
	v_mov_b32_e32 v163, v117
	v_mov_b32_e32 v164, v117
	v_mov_b32_e32 v165, v162
	v_mov_b32_e32 v166, v162
	v_permlane32_swap_b32_e32 v163, v164
	s_nop 0
	v_permlane32_swap_b32_e32 v165, v166
	v_add_f32_e32 v167, v163, v164
	v_add_f32_e32 v168, v165, v166
	v_cndmask_b32_e64 v167, v168, v167, s[4:5]
	v_add_f32_e32 v167, 0, v167
	v_ashrrev_i32_e32 v168, 31, v167
	v_bitop3_b32 v167, v168, v167, s82 bitop3:0x36
	v_mov_b32_e32 v163, v116
	v_mov_b32_e32 v164, v116
	v_mov_b32_e32 v165, v161
	v_mov_b32_e32 v166, v161
	v_lshrrev_b32_e32 v168, 22, v167
	v_permlane32_swap_b32_e32 v163, v164
	v_permlane32_swap_b32_e32 v165, v166
	v_cmp_eq_u32_e32 vcc, v168, v108
	s_and_saveexec_b64 s[26:27], vcc
	s_cbranch_execz .LBB0_3245
	v_lshrrev_b32_e32 v168, 11, v167
	v_lshrrev_b32_e32 v167, 8, v167
	v_and_b32_e32 v168, 0x7fc, v168
	v_and_b32_e32 v167, 16, v167
	v_add_u32_e32 v168, v123, v168
	v_lshlrev_b32_e64 v167, v167, 1
	ds_add_u32 v168, v167

; #define MFMA32(a, b, c) __builtin_amdgcn_mfma_f32_32x32x16_bf16((a), (b), (c), 0, 0, 0)
; DI float xhalf_sum(float v) { const auto r = __builtin_amdgcn_permlane32_swap(__float_as_uint(v), __float_as_uint(v), false, false); return __uint_as_float(r[0]) + __uint_as_float(r[1]); }
; DI void phase_index(const Params& p, unsigned char* lds) {
;     ...
;         auto mma = [&](f32x16& s, unsigned off) {
; #pragma unroll
;             for (int i = 0; i < 16; ++i) s[i] = 0.f;
; #pragma unroll
;             for (int ks = 0; ks < 4; ++ks) { const bf16x8 kf = *(const bf16x8*)(lds + off + ks * 32); s = MFMA32(qf[ks], kf, s); }
;         };
;         auto proc = [&](auto PASSC, auto DIAGC, const f32x16& s, int k0, int kb) {
;             constexpr int PASS = decltype(PASSC)::value; constexpr bool DIAG = decltype(DIAGC)::value != 0;
;             f32x4 tot;
; #pragma unroll
;             for (int q = 0; q < 4; ++q) {
;                 float pr = 0.f;
; #pragma unroll
;                 for (int e = 0; e < 4; ++e) pr += wq[q][e] * fmaxf(s[4 * q + e], 0.f);
;                 tot[q] = xhalf_sum(pr);
.LBB0_3520:
	s_mul_i32 s26, s1, 0x2400
	v_add_u32_e32 v163, s26, v161
	ds_read_b128 v[18:21], v163 offset:4608
	ds_read_b128 v[114:117], v163 offset:4640
	s_nop 2
	s_waitcnt lgkmcnt(1)
	v_mfma_f32_32x32x16_bf16 v[18:33], v[42:45], v[18:21], 0
	v_max_f32_e32 v168, 0, v6
	v_max_f32_e32 v170, v8, v8
	v_max_f32_e32 v172, 0, v2
	v_max_f32_e32 v173, 0, v3
	s_waitcnt lgkmcnt(0)
	v_mfma_f32_32x32x16_bf16 v[18:33], v[34:37], v[114:117], v[18:33]
	ds_read_b128 v[114:117], v163 offset:4672
	v_max_f32_e32 v174, 0, v4
	v_max_f32_e32 v175, 0, v5
	v_max_f32_e32 v169, 0, v7
	ds_read_b128 v[164:167], v163 offset:4704
	s_add_i32 s36, s1, s96
	s_cmp_lg_u32 s36, s91
	s_waitcnt lgkmcnt(1)
	v_mfma_f32_32x32x16_bf16 v[18:33], v[38:41], v[114:117], v[18:33]
	v_fma_f32 v115, v54, v168, 0
	v_fmac_f32_e32 v115, v55, v169
	v_max_f32_e32 v116, 0, v170
	v_fmac_f32_e32 v115, v56, v116
	v_max_f32_e32 v116, 0, v9
	v_fmac_f32_e32 v115, v57, v116
	v_max_f32_e32 v116, 0, v10
	v_fma_f32 v116, v58, v116, 0
	v_max_f32_e32 v117, 0, v11
	v_fmac_f32_e32 v116, v59, v117
	v_max_f32_e32 v117, 0, v12
	v_fmac_f32_e32 v116, v60, v117
	v_max_f32_e32 v117, 0, v13
	s_waitcnt lgkmcnt(0)
	v_mfma_f32_32x32x16_bf16 v[18:33], v[46:49], v[164:167], v[18:33]
	v_fmac_f32_e32 v116, v61, v117
	v_max_f32_e32 v117, 0, v14
	v_fma_f32 v117, v62, v117, 0
	v_max_f32_e32 v164, 0, v15
	v_fmac_f32_e32 v117, v63, v164
	v_fma_f32 v114, v50, v172, 0
	v_max_f32_e32 v164, 0, v16
	v_fmac_f32_e32 v114, v51, v173
	v_fmac_f32_e32 v117, v64, v164
	s_cselect_b64 s[58:59], -1, 0
	v_fmac_f32_e32 v114, v52, v174
	v_max_f32_e32 v164, 0, v17
	v_fmac_f32_e32 v114, v53, v175
	v_fmac_f32_e32 v117, v65, v164
	s_mov_b64 s[26:27], -1
	s_and_b64 vcc, exec, s[58:59]
	s_cbranch_vccnz .LBB0_3555
	s_lshl_b32 s28, s36, 6
	s_andn2_b64 vcc, exec, s[26:27]
	v_or_b32_e32 v164, s28, v194
	s_cbranch_vccz .LBB0_3556
